# FFN-in GEMM: next unit first tile LDS-DMA issued before the epilogue
# baseline (speedup 1.0000x reference)
; #define STAGE_A(P, br, kt) do { const u16* _g = Ab + (long)(br) * lda + (long)(kt) * 64; GLDS(_g + ao0, (char*)(P) + tid * 16); GLDS(_g + ao1, (char*)(P) + tid * 16 + 8192); } while (0)
; #define STAGE_B(P, br, kt) do { const u16* _g = Bb + (long)(br) * ldb + (long)(kt) * 64; GLDS(_g + bo0, (char*)(P) + tid * 16); GLDS(_g + bo1, (char*)(P) + tid * 16 + 8192); } while (0)
; template <int EPI>
; DI void gemm_unit(const GemmP& g, int pm, int pn) {
;     ...
;   int r0_, c0_, r1_, c1_; stage_rc(tid * 16, r0_, c0_); stage_rc(tid * 16 + 8192, r1_, c1_);
;   const long ao0 = (long)r0_ * lda + c0_, ao1 = (long)r1_ * lda + c1_, bo0 = (long)r0_ * ldb + c0_, bo1 = (long)r1_ * ldb + c1_;
;   f32x4 acc[2][2][4][2];
; #pragma unroll
;   for (int a = 0; a < 2; ++a)
; #pragma unroll
;     for (int b = 0; b < 2; ++b)
; #pragma unroll
;       for (int m = 0; m < 4; ++m)
; #pragma unroll
;         for (int n = 0; n < 2; ++n) acc[a][b][m][n] = (f32x4){0.f, 0.f, 0.f, 0.f};
;   bf16x8 At[4][2], B0[2][2], B1[2][2];
;   const int nt = g.K >> 6;
;   STAGE_B(SB(0, 0), bcol, 0); STAGE_A(SA(0, 0), brow, 0);
;   STAGE_B(SB(0, 1), bcol + 128, 0); STAGE_A(SA(0, 1), brow + 128, 0);
; DI bool unit_of(int L, int nM, int nN, int& pm, int& pn) {
;   const int nwg = nM * nN; if (L >= nwg) return false;
;   int wgid = L; { const int q = nwg / 8, r = nwg % 8, xcd = wgid % 8, off = wgid / 8; wgid = (xcd < r ? xcd * (q + 1) : r * (q + 1) + (xcd - r) * q) + off; }
;   const int nig = 8 * nN, gid = wgid / nig, fm = gid * 8, gsz = (nM - fm) < 8 ? (nM - fm) : 8;
;   pm = fm + ((wgid % nig) % gsz); pn = (wgid % nig) / gsz; return true;
; }
.LBB0_150:
	s_or_b64 exec, exec, s[10:11]
	v_readlane_b32 s32, v254, 1
	s_nop 3
	s_add_i32 s32, s13, s32
	s_cmpk_gt_i32 s32, 0xaff
	s_cbranch_scc1 .Lff_pf_skip
	v_mov_b32_e32 v146, v201
	s_ashr_i32 s38, s32, 31
	v_ashrrev_i32_e32 v148, 31, v146
	v_lshrrev_b32_e32 v148, 26, v148
	v_add_u32_e32 v148, v146, v148
	v_ashrrev_i32_e32 v149, 6, v148
	v_bfe_i32 v148, v146, 27, 1
	v_lshlrev_b32_e32 v168, 4, v146
	v_lshrrev_b32_e32 v148, 22, v148
	v_add_u32_e32 v148, v168, v148
	v_and_b32_e32 v148, 0xfffffc00, v148
	v_sub_u32_e32 v148, v168, v148
	v_lshrrev_b32_e32 v150, 4, v148
	v_bitop3_b32 v150, v150, v148, 32 bitop3:0x6c
	v_ashrrev_i32_e32 v148, 31, v148
	v_lshrrev_b32_e32 v148, 26, v148
	v_lshlrev_b32_e32 v151, 3, v149
	v_add_u32_e32 v148, v150, v148
	s_lshr_b32 s38, s38, 29
	v_and_b32_e32 v151, -16, v151
	v_ashrrev_i32_e32 v152, 6, v148
	s_add_i32 s38, s32, s38
	v_add_u32_e32 v148, v152, v151
	v_mul_i32_i24_e32 v151, 64, v152
	s_ashr_i32 s39, s38, 3
	s_and_b32 s38, s38, -8
	v_lshlrev_b32_e32 v149, 5, v149
	v_sub_u32_e32 v150, v150, v151
	s_sub_i32 s38, s32, s38
	v_and_b32_e32 v149, 32, v149
	v_ashrrev_i16_sdwa v150, v218, sext(v150) dst_sel:DWORD dst_unused:UNUSED_PAD src0_sel:DWORD src1_sel:BYTE_0
	s_cmp_lt_i32 s38, 0
	s_movk_i32 s40, 0x161
	v_add_u32_sdwa v150, v149, sext(v150) dst_sel:DWORD dst_unused:UNUSED_PAD src0_sel:DWORD src1_sel:WORD_0
	v_add_u32_e32 v149, 0x2000, v168
	s_cselect_b32 s40, s40, 0x160
	v_ashrrev_i32_e32 v151, 31, v149
	s_mul_i32 s38, s40, s38
	v_lshrrev_b32_e32 v151, 22, v151
	s_add_i32 s38, s38, s39
	v_add_u32_e32 v151, v149, v151
	s_mul_hi_i32 s39, s38, 0x2e8ba2e9
	v_ashrrev_i32_e32 v151, 10, v151
	s_lshr_b32 s40, s39, 31
	s_ashr_i32 s39, s39, 6
	v_mul_i32_i24_e32 v152, 0x400, v151
	s_add_i32 s39, s39, s40
	v_sub_u32_e32 v149, v149, v152
	s_mul_i32 s40, s39, 0x160
	v_lshrrev_b32_e32 v152, 4, v149
	s_sub_i32 s38, s38, s40
	v_bitop3_b32 v149, v152, v149, 32 bitop3:0x6c
	s_sext_i32_i16 s40, s38
	v_ashrrev_i32_e32 v153, 31, v149
	s_bfe_u32 s40, s40, 0x3001c
	v_lshrrev_b32_e32 v153, 26, v153
	s_add_i32 s40, s38, s40
	v_add_u32_e32 v153, v149, v153
	s_sext_i32_i16 s41, s40
	s_and_b32 s40, s40, 0xfff8
	v_ashrrev_i32_e32 v154, 6, v153
	v_and_b32_e32 v153, 0xc0, v153
	s_sub_i32 s38, s38, s40
	s_ashr_i32 s50, s41, 3
	v_lshlrev_b32_e32 v152, 3, v151
	v_lshlrev_b32_e32 v151, 5, v151
	v_sub_u32_e32 v149, v149, v153
	s_sext_i32_i16 s38, s38
	v_and_b32_e32 v152, -16, v152
	v_and_b32_e32 v151, 32, v151
	v_ashrrev_i16_sdwa v149, v218, sext(v149) dst_sel:DWORD dst_unused:UNUSED_PAD src0_sel:DWORD src1_sel:BYTE_0
	s_lshl_b32 s46, s50, 8
	s_lshl_b32 s39, s39, 11
	s_lshl_b32 s38, s38, 8
	v_add_u32_e32 v152, v154, v152
	v_add_u32_sdwa v154, v151, sext(v149) dst_sel:DWORD dst_unused:UNUSED_PAD src0_sel:DWORD src1_sel:WORD_0
	v_ashrrev_i32_e32 v149, 31, v148
	s_ashr_i32 s47, s46, 31
	s_add_i32 s38, s38, s39
	v_ashrrev_i32_e32 v151, 31, v150
	v_lshlrev_b64 v[156:157], 11, v[148:149]
	s_lshl_b64 s[40:41], s[46:47], 12
	v_readlane_b32 s39, v254, 21
	v_ashrrev_i32_e32 v153, 31, v152
	v_lshl_add_u64 v[156:157], v[156:157], 0, v[150:151]
	s_add_u32 s44, s20, s40
	v_add_u32_e32 v178, s39, v168
	v_ashrrev_i32_e32 v155, 31, v154
	v_lshlrev_b64 v[158:159], 11, v[152:153]
	s_addc_u32 s45, s21, s41
	v_lshlrev_b64 v[170:171], 1, v[156:157]
	v_readfirstlane_b32 s39, v178
	v_add_u32_e32 v179, 0x2000, v178
	v_lshl_add_u64 v[158:159], v[158:159], 0, v[154:155]
	v_lshl_add_u64 v[156:157], s[44:45], 0, v[170:171]
	s_mov_b32 m0, s39
	v_readfirstlane_b32 s39, v179
	global_load_lds_dwordx4 v[156:157], off
	v_lshlrev_b64 v[172:173], 1, v[158:159]
	s_mov_b32 m0, s39
	s_ashr_i32 s39, s38, 31
	v_lshl_add_u64 v[158:159], s[44:45], 0, v[172:173]
	s_lshl_b64 s[44:45], s[38:39], 12
	s_add_u32 s48, s66, s44
	s_addc_u32 s49, s67, s45
	s_bitset1_b32 s46, 7
	s_ashr_i32 s47, s46, 31
	v_add_u32_e32 v180, 0, v168
	s_lshl_b64 s[46:47], s[46:47], 12
	v_readfirstlane_b32 s39, v180
	v_add_u32_e32 v181, 0x2000, v180
	s_add_u32 s46, s20, s46
	global_load_lds_dwordx4 v[158:159], off
	v_lshl_add_u64 v[160:161], s[48:49], 0, v[170:171]
	s_mov_b32 m0, s39
	v_readfirstlane_b32 s39, v181
	s_addc_u32 s47, s21, s47
	global_load_lds_dwordx4 v[160:161], off
	s_mov_b32 m0, s39
	v_lshl_add_u64 v[166:167], s[46:47], 0, v[170:171]
	v_readlane_b32 s39, v254, 22
	v_lshl_add_u64 v[164:165], s[46:47], 0, v[172:173]
	s_or_b32 s46, s38, 0x80
	v_add_u32_e32 v182, s39, v168
	s_ashr_i32 s47, s46, 31
	v_lshl_add_u64 v[162:163], s[48:49], 0, v[172:173]
	v_readfirstlane_b32 s39, v182
	v_add_u32_e32 v183, 0x2000, v182
	s_lshl_b64 s[46:47], s[46:47], 12
	global_load_lds_dwordx4 v[162:163], off
	s_mov_b32 m0, s39
	v_readfirstlane_b32 s39, v183
	s_add_u32 s46, s66, s46
	v_add_u32_e32 v184, 0x4000, v180
	global_load_lds_dwordx4 v[166:167], off
	s_mov_b32 m0, s39
	s_addc_u32 s47, s67, s47
	v_readfirstlane_b32 s39, v184
	v_add_u32_e32 v185, 0x6000, v180
	global_load_lds_dwordx4 v[164:165], off
	v_lshl_add_u64 v[174:175], s[46:47], 0, v[170:171]
	s_mov_b32 m0, s39
	v_readfirstlane_b32 s39, v185
	global_load_lds_dwordx4 v[174:175], off
	v_lshl_add_u64 v[176:177], s[46:47], 0, v[172:173]
	s_mov_b32 m0, s39
	v_ashrrev_i32_e32 v169, 8, v146
	global_load_lds_dwordx4 v[176:177], off
; template <int EPI>
; DI void gemm_unit(const GemmP& g, int pm, int pn) {
;     ...
;     const int hc0 = pn * 128 + wc * 32 + fq * 4;
; #pragma unroll
;     for (int ai = 0; ai < 2; ++ai)
; #pragma unroll
;       for (int m = 0; m < 4; ++m) {
;         u16* rowp = g.Cb + (size_t)(row0 + ai * 128 + m * 16) * g.ldc + hc0;
; #pragma unroll
;         for (int n = 0; n < 2; ++n) {
;           const f32x4 gv = acc[ai][0][m][n], uv = acc[ai][1][m][n];
;           float hv[4];
; #pragma unroll
;           for (int e = 0; e < 4; ++e) hv[e] = gv[e] * __builtin_amdgcn_rcpf(1.f + __builtin_amdgcn_exp2f(-LOG2E * gv[e])) * uv[e];
;           uint2 o; o.x = pk2(hv[0], hv[1]); o.y = pk2(hv[2], hv[3]);
;           *(uint2*)(rowp + n * 16) = o;
;         }
;       }
.Lff_pf_skip:
	v_mul_f32_e32 v136, 0xbfb8aa3b, v122
	v_mul_f32_e32 v137, 0xbfb8aa3b, v123
	v_exp_f32_e32 v136, v136
	v_exp_f32_e32 v137, v137
	v_lshlrev_b32_e32 v0, 5, v143
	v_lshlrev_b32_e32 v130, 2, v144
	v_add_f32_e32 v136, 1.0, v136
	v_add_f32_e32 v137, 1.0, v137
	v_rcp_f32_e32 v136, v136
	v_rcp_f32_e32 v137, v137
	s_lshl_b32 s9, s22, 7
	v_or3_b32 v132, s9, v0, v130
	v_or_b32_e32 v0, s8, v142
	v_pk_mul_f32 v[122:123], v[122:123], v[136:137]
	v_add_u32_e32 v0, v0, v145
	v_pk_mul_f32 v[122:123], v[122:123], v[126:127]
	v_mul_f32_e32 v126, 0xbfb8aa3b, v124
	v_mul_f32_e32 v127, 0xbfb8aa3b, v125
	v_exp_f32_e32 v126, v126
	v_exp_f32_e32 v127, v127
	v_ashrrev_i32_e32 v133, 31, v132
	v_mov_b64_e32 v[130:131], s[6:7]
	v_add_f32_e32 v126, 1.0, v126
	v_add_f32_e32 v127, 1.0, v127
	v_rcp_f32_e32 v126, v126
	v_rcp_f32_e32 v127, v127
	s_movk_i32 s10, 0x2c00
	v_mad_i64_i32 v[134:135], s[8:9], v0, s10, v[130:131]
	v_pk_mul_f32 v[124:125], v[124:125], v[126:127]
	v_lshlrev_b64 v[132:133], 1, v[132:133]
	v_pk_mul_f32 v[124:125], v[124:125], v[128:129]
	v_lshl_add_u64 v[134:135], v[134:135], 0, v[132:133]
	v_cvt_pk_bf16_f32 v122, v122, v123
	v_cvt_pk_bf16_f32 v123, v124, v125
	global_store_dwordx2 v[134:135], v[122:123], off
	v_mul_f32_e32 v122, 0xbfb8aa3b, v114
	v_mul_f32_e32 v123, 0xbfb8aa3b, v115
	v_exp_f32_e32 v122, v122
	v_exp_f32_e32 v123, v123
	v_add_f32_e32 v122, 1.0, v122
	v_add_f32_e32 v123, 1.0, v123
	v_rcp_f32_e32 v122, v122
	v_rcp_f32_e32 v123, v123
	s_nop 0
	v_pk_mul_f32 v[114:115], v[114:115], v[122:123]
	s_nop 0
	v_pk_mul_f32 v[114:115], v[114:115], v[118:119]
	v_mul_f32_e32 v118, 0xbfb8aa3b, v116
	v_mul_f32_e32 v119, 0xbfb8aa3b, v117
	v_exp_f32_e32 v118, v118
	v_exp_f32_e32 v119, v119
	v_cvt_pk_bf16_f32 v114, v114, v115
	v_add_f32_e32 v118, 1.0, v118
	v_add_f32_e32 v119, 1.0, v119
	v_rcp_f32_e32 v118, v118
	v_rcp_f32_e32 v119, v119
	s_nop 0
	v_pk_mul_f32 v[116:117], v[116:117], v[118:119]
	s_nop 0
	v_pk_mul_f32 v[116:117], v[116:117], v[120:121]
	s_nop 0
	v_cvt_pk_bf16_f32 v115, v116, v117
	v_mul_f32_e32 v116, 0xbfb8aa3b, v106
	v_mul_f32_e32 v117, 0xbfb8aa3b, v107
	v_exp_f32_e32 v116, v116
	v_exp_f32_e32 v117, v117
	global_store_dwordx2 v[134:135], v[114:115], off offset:32
	v_or_b32_e32 v114, 16, v0
	v_add_f32_e32 v116, 1.0, v116
	v_add_f32_e32 v117, 1.0, v117
	v_rcp_f32_e32 v116, v116
	v_rcp_f32_e32 v117, v117
	v_mad_i64_i32 v[114:115], s[8:9], v114, s10, v[130:131]
	v_lshl_add_u64 v[114:115], v[114:115], 0, v[132:133]
	v_pk_mul_f32 v[106:107], v[106:107], v[116:117]
	s_nop 0
	v_pk_mul_f32 v[106:107], v[106:107], v[110:111]
	v_mul_f32_e32 v110, 0xbfb8aa3b, v108
	v_mul_f32_e32 v111, 0xbfb8aa3b, v109
	v_exp_f32_e32 v110, v110
	v_exp_f32_e32 v111, v111
	v_cvt_pk_bf16_f32 v106, v106, v107
	v_add_f32_e32 v110, 1.0, v110
	v_add_f32_e32 v111, 1.0, v111
	v_rcp_f32_e32 v110, v110
	v_rcp_f32_e32 v111, v111
	s_nop 0
	v_pk_mul_f32 v[108:109], v[108:109], v[110:111]
	s_nop 0
	v_pk_mul_f32 v[108:109], v[108:109], v[112:113]
	s_nop 0
	v_cvt_pk_bf16_f32 v107, v108, v109
	global_store_dwordx2 v[114:115], v[106:107], off
	v_mul_f32_e32 v106, 0xbfb8aa3b, v98
	v_mul_f32_e32 v107, 0xbfb8aa3b, v99
	v_exp_f32_e32 v106, v106
	v_exp_f32_e32 v107, v107
	v_add_f32_e32 v106, 1.0, v106
	v_add_f32_e32 v107, 1.0, v107
	v_rcp_f32_e32 v106, v106
	v_rcp_f32_e32 v107, v107
	s_nop 0
	v_pk_mul_f32 v[98:99], v[98:99], v[106:107]
	s_nop 0
	v_pk_mul_f32 v[98:99], v[98:99], v[102:103]
	v_mul_f32_e32 v102, 0xbfb8aa3b, v100
	v_mul_f32_e32 v103, 0xbfb8aa3b, v101
	v_exp_f32_e32 v102, v102
	v_exp_f32_e32 v103, v103
	v_cvt_pk_bf16_f32 v98, v98, v99
	v_add_f32_e32 v102, 1.0, v102
	v_add_f32_e32 v103, 1.0, v103
	v_rcp_f32_e32 v102, v102
	v_rcp_f32_e32 v103, v103
	s_nop 0
	v_pk_mul_f32 v[100:101], v[100:101], v[102:103]
	s_nop 0
	v_pk_mul_f32 v[100:101], v[100:101], v[104:105]
	s_nop 0
	v_cvt_pk_bf16_f32 v99, v100, v101
	v_mul_f32_e32 v100, 0xbfb8aa3b, v90
	v_mul_f32_e32 v101, 0xbfb8aa3b, v91
	v_exp_f32_e32 v100, v100
	v_exp_f32_e32 v101, v101
	global_store_dwordx2 v[114:115], v[98:99], off offset:32
	v_or_b32_e32 v98, 32, v0
	v_add_f32_e32 v100, 1.0, v100
	v_add_f32_e32 v101, 1.0, v101
	v_rcp_f32_e32 v100, v100
	v_rcp_f32_e32 v101, v101
	v_mad_i64_i32 v[98:99], s[8:9], v98, s10, v[130:131]
	v_lshl_add_u64 v[98:99], v[98:99], 0, v[132:133]
	v_pk_mul_f32 v[90:91], v[90:91], v[100:101]
	s_nop 0
	v_pk_mul_f32 v[90:91], v[90:91], v[94:95]
	v_mul_f32_e32 v94, 0xbfb8aa3b, v92
	v_mul_f32_e32 v95, 0xbfb8aa3b, v93
	v_exp_f32_e32 v94, v94
	v_exp_f32_e32 v95, v95
	v_cvt_pk_bf16_f32 v90, v90, v91
	v_add_f32_e32 v94, 1.0, v94
	v_add_f32_e32 v95, 1.0, v95
	v_rcp_f32_e32 v94, v94
	v_rcp_f32_e32 v95, v95
	s_nop 0
	v_pk_mul_f32 v[92:93], v[92:93], v[94:95]
	s_nop 0
	v_pk_mul_f32 v[92:93], v[92:93], v[96:97]
	s_nop 0
	v_cvt_pk_bf16_f32 v91, v92, v93
	global_store_dwordx2 v[98:99], v[90:91], off
	v_mul_f32_e32 v90, 0xbfb8aa3b, v82
	v_mul_f32_e32 v91, 0xbfb8aa3b, v83
	v_exp_f32_e32 v90, v90
	v_exp_f32_e32 v91, v91
	v_add_f32_e32 v90, 1.0, v90
	v_add_f32_e32 v91, 1.0, v91
	v_rcp_f32_e32 v90, v90
	v_rcp_f32_e32 v91, v91
	s_nop 0
	v_pk_mul_f32 v[82:83], v[82:83], v[90:91]
	s_nop 0
	v_pk_mul_f32 v[82:83], v[82:83], v[86:87]
	v_mul_f32_e32 v86, 0xbfb8aa3b, v84
	v_mul_f32_e32 v87, 0xbfb8aa3b, v85
	v_exp_f32_e32 v86, v86
	v_exp_f32_e32 v87, v87
	v_cvt_pk_bf16_f32 v82, v82, v83
	v_add_f32_e32 v86, 1.0, v86
	v_add_f32_e32 v87, 1.0, v87
	v_rcp_f32_e32 v86, v86
	v_rcp_f32_e32 v87, v87
	s_nop 0
	v_pk_mul_f32 v[84:85], v[84:85], v[86:87]
	s_nop 0
	v_pk_mul_f32 v[84:85], v[84:85], v[88:89]
	s_nop 0
	v_cvt_pk_bf16_f32 v83, v84, v85
	v_mul_f32_e32 v84, 0xbfb8aa3b, v74
	v_mul_f32_e32 v85, 0xbfb8aa3b, v75
; template <int EPI>
; DI void gemm_unit(const GemmP& g, int pm, int pn) {
;     ...
;     const int hc0 = pn * 128 + wc * 32 + fq * 4;
; #pragma unroll
;     for (int ai = 0; ai < 2; ++ai)
; #pragma unroll
;       for (int m = 0; m < 4; ++m) {
;         u16* rowp = g.Cb + (size_t)(row0 + ai * 128 + m * 16) * g.ldc + hc0;
; #pragma unroll
;         for (int n = 0; n < 2; ++n) {
;           const f32x4 gv = acc[ai][0][m][n], uv = acc[ai][1][m][n];
;           float hv[4];
; #pragma unroll
;           for (int e = 0; e < 4; ++e) hv[e] = gv[e] * __builtin_amdgcn_rcpf(1.f + __builtin_amdgcn_exp2f(-LOG2E * gv[e])) * uv[e];
;           uint2 o; o.x = pk2(hv[0], hv[1]); o.y = pk2(hv[2], hv[3]);
;           *(uint2*)(rowp + n * 16) = o;
;         }
;       }
	v_exp_f32_e32 v84, v84
	v_exp_f32_e32 v85, v85
	global_store_dwordx2 v[98:99], v[82:83], off offset:32
	v_or_b32_e32 v82, 48, v0
	v_add_f32_e32 v84, 1.0, v84
	v_add_f32_e32 v85, 1.0, v85
	v_rcp_f32_e32 v84, v84
	v_rcp_f32_e32 v85, v85
	v_mad_i64_i32 v[82:83], s[8:9], v82, s10, v[130:131]
	v_lshl_add_u64 v[82:83], v[82:83], 0, v[132:133]
	v_pk_mul_f32 v[74:75], v[74:75], v[84:85]
	s_nop 0
	v_pk_mul_f32 v[74:75], v[74:75], v[78:79]
	v_mul_f32_e32 v78, 0xbfb8aa3b, v76
	v_mul_f32_e32 v79, 0xbfb8aa3b, v77
	v_exp_f32_e32 v78, v78
	v_exp_f32_e32 v79, v79
	v_cvt_pk_bf16_f32 v74, v74, v75
	v_add_f32_e32 v78, 1.0, v78
	v_add_f32_e32 v79, 1.0, v79
	v_rcp_f32_e32 v78, v78
	v_rcp_f32_e32 v79, v79
	s_nop 0
	v_pk_mul_f32 v[76:77], v[76:77], v[78:79]
	s_nop 0
	v_pk_mul_f32 v[76:77], v[76:77], v[80:81]
	s_nop 0
	v_cvt_pk_bf16_f32 v75, v76, v77
	global_store_dwordx2 v[82:83], v[74:75], off
	v_mul_f32_e32 v74, 0xbfb8aa3b, v66
	v_mul_f32_e32 v75, 0xbfb8aa3b, v67
	v_exp_f32_e32 v74, v74
	v_exp_f32_e32 v75, v75
	v_add_f32_e32 v74, 1.0, v74
	v_add_f32_e32 v75, 1.0, v75
	v_rcp_f32_e32 v74, v74
	v_rcp_f32_e32 v75, v75
	s_nop 0
	v_pk_mul_f32 v[66:67], v[66:67], v[74:75]
	s_nop 0
	v_pk_mul_f32 v[66:67], v[66:67], v[70:71]
	v_mul_f32_e32 v70, 0xbfb8aa3b, v68
	v_mul_f32_e32 v71, 0xbfb8aa3b, v69
	v_exp_f32_e32 v70, v70
	v_exp_f32_e32 v71, v71
	v_cvt_pk_bf16_f32 v66, v66, v67
	v_add_f32_e32 v70, 1.0, v70
	v_add_f32_e32 v71, 1.0, v71
	v_rcp_f32_e32 v70, v70
	v_rcp_f32_e32 v71, v71
	s_nop 0
	v_pk_mul_f32 v[68:69], v[68:69], v[70:71]
	s_nop 0
	v_pk_mul_f32 v[68:69], v[68:69], v[72:73]
	s_nop 0
	v_cvt_pk_bf16_f32 v67, v68, v69
	v_mul_f32_e32 v68, 0xbfb8aa3b, v58
	v_mul_f32_e32 v69, 0xbfb8aa3b, v59
	v_exp_f32_e32 v68, v68
	v_exp_f32_e32 v69, v69
	global_store_dwordx2 v[82:83], v[66:67], off offset:32
	v_add_u32_e32 v66, 0x80, v0
	v_add_f32_e32 v68, 1.0, v68
	v_add_f32_e32 v69, 1.0, v69
	v_rcp_f32_e32 v68, v68
	v_rcp_f32_e32 v69, v69
	v_mad_i64_i32 v[66:67], s[8:9], v66, s10, v[130:131]
	v_lshl_add_u64 v[66:67], v[66:67], 0, v[132:133]
	v_pk_mul_f32 v[58:59], v[58:59], v[68:69]
	s_nop 0
	v_pk_mul_f32 v[58:59], v[58:59], v[62:63]
	v_mul_f32_e32 v62, 0xbfb8aa3b, v60
	v_mul_f32_e32 v63, 0xbfb8aa3b, v61
	v_exp_f32_e32 v62, v62
	v_exp_f32_e32 v63, v63
	v_cvt_pk_bf16_f32 v58, v58, v59
	v_add_f32_e32 v62, 1.0, v62
	v_add_f32_e32 v63, 1.0, v63
	v_rcp_f32_e32 v62, v62
	v_rcp_f32_e32 v63, v63
	s_nop 0
	v_pk_mul_f32 v[60:61], v[60:61], v[62:63]
	s_nop 0
	v_pk_mul_f32 v[60:61], v[60:61], v[64:65]
	s_nop 0
	v_cvt_pk_bf16_f32 v59, v60, v61
	global_store_dwordx2 v[66:67], v[58:59], off
	v_mul_f32_e32 v58, 0xbfb8aa3b, v50
	v_mul_f32_e32 v59, 0xbfb8aa3b, v51
	v_exp_f32_e32 v58, v58
	v_exp_f32_e32 v59, v59
	v_add_f32_e32 v58, 1.0, v58
	v_add_f32_e32 v59, 1.0, v59
	v_rcp_f32_e32 v58, v58
	v_rcp_f32_e32 v59, v59
	s_nop 0
	v_pk_mul_f32 v[50:51], v[50:51], v[58:59]
	s_nop 0
	v_pk_mul_f32 v[50:51], v[50:51], v[54:55]
	v_mul_f32_e32 v54, 0xbfb8aa3b, v52
	v_mul_f32_e32 v55, 0xbfb8aa3b, v53
	v_exp_f32_e32 v54, v54
	v_exp_f32_e32 v55, v55
	v_cvt_pk_bf16_f32 v50, v50, v51
	v_add_f32_e32 v54, 1.0, v54
	v_add_f32_e32 v55, 1.0, v55
	v_rcp_f32_e32 v54, v54
	v_rcp_f32_e32 v55, v55
	s_nop 0
	v_pk_mul_f32 v[52:53], v[52:53], v[54:55]
	s_nop 0
	v_pk_mul_f32 v[52:53], v[52:53], v[56:57]
	s_nop 0
	v_cvt_pk_bf16_f32 v51, v52, v53
	v_mul_f32_e32 v52, 0xbfb8aa3b, v42
	v_mul_f32_e32 v53, 0xbfb8aa3b, v43
	v_exp_f32_e32 v52, v52
	v_exp_f32_e32 v53, v53
	global_store_dwordx2 v[66:67], v[50:51], off offset:32
	v_add_u32_e32 v50, 0x90, v0
	v_add_f32_e32 v52, 1.0, v52
	v_add_f32_e32 v53, 1.0, v53
	v_rcp_f32_e32 v52, v52
	v_rcp_f32_e32 v53, v53
	v_mad_i64_i32 v[50:51], s[8:9], v50, s10, v[130:131]
	v_lshl_add_u64 v[50:51], v[50:51], 0, v[132:133]
	v_pk_mul_f32 v[42:43], v[42:43], v[52:53]
	s_nop 0
	v_pk_mul_f32 v[42:43], v[42:43], v[46:47]
	v_mul_f32_e32 v46, 0xbfb8aa3b, v44
	v_mul_f32_e32 v47, 0xbfb8aa3b, v45
	v_exp_f32_e32 v46, v46
	v_exp_f32_e32 v47, v47
	v_cvt_pk_bf16_f32 v42, v42, v43
	v_add_f32_e32 v46, 1.0, v46
	v_add_f32_e32 v47, 1.0, v47
	v_rcp_f32_e32 v46, v46
	v_rcp_f32_e32 v47, v47
	s_nop 0
	v_pk_mul_f32 v[44:45], v[44:45], v[46:47]
	s_nop 0
	v_pk_mul_f32 v[44:45], v[44:45], v[48:49]
	s_nop 0
	v_cvt_pk_bf16_f32 v43, v44, v45
	global_store_dwordx2 v[50:51], v[42:43], off
	v_mul_f32_e32 v42, 0xbfb8aa3b, v34
	v_mul_f32_e32 v43, 0xbfb8aa3b, v35
	v_exp_f32_e32 v42, v42
	v_exp_f32_e32 v43, v43
	v_add_f32_e32 v42, 1.0, v42
	v_add_f32_e32 v43, 1.0, v43
	v_rcp_f32_e32 v42, v42
	v_rcp_f32_e32 v43, v43
	s_nop 0
	v_pk_mul_f32 v[34:35], v[34:35], v[42:43]
	s_nop 0
	v_pk_mul_f32 v[34:35], v[34:35], v[38:39]
	v_mul_f32_e32 v38, 0xbfb8aa3b, v36
	v_mul_f32_e32 v39, 0xbfb8aa3b, v37
	v_exp_f32_e32 v38, v38
	v_exp_f32_e32 v39, v39
	v_cvt_pk_bf16_f32 v34, v34, v35
	v_add_f32_e32 v38, 1.0, v38
	v_add_f32_e32 v39, 1.0, v39
	v_rcp_f32_e32 v38, v38
	v_rcp_f32_e32 v39, v39
	s_nop 0
	v_pk_mul_f32 v[36:37], v[36:37], v[38:39]
	s_nop 0
	v_pk_mul_f32 v[36:37], v[36:37], v[40:41]
	s_nop 0
	v_cvt_pk_bf16_f32 v35, v36, v37
	v_mul_f32_e32 v36, 0xbfb8aa3b, v26
	v_mul_f32_e32 v37, 0xbfb8aa3b, v27
	v_exp_f32_e32 v36, v36
	v_exp_f32_e32 v37, v37
	global_store_dwordx2 v[50:51], v[34:35], off offset:32
	v_add_u32_e32 v34, 0xa0, v0
	v_add_f32_e32 v36, 1.0, v36
	v_add_f32_e32 v37, 1.0, v37
	v_rcp_f32_e32 v36, v36
	v_rcp_f32_e32 v37, v37
	v_mad_i64_i32 v[34:35], s[8:9], v34, s10, v[130:131]
	v_lshl_add_u64 v[34:35], v[34:35], 0, v[132:133]
	v_pk_mul_f32 v[26:27], v[26:27], v[36:37]
	v_add_u32_e32 v0, 0xb0, v0
	v_pk_mul_f32 v[26:27], v[26:27], v[30:31]
	v_mul_f32_e32 v30, 0xbfb8aa3b, v28
	v_mul_f32_e32 v31, 0xbfb8aa3b, v29
	v_exp_f32_e32 v30, v30
; #define STAGE_A(P, br, kt) do { const u16* _g = Ab + (long)(br) * lda + (long)(kt) * 64; GLDS(_g + ao0, (char*)(P) + tid * 16); GLDS(_g + ao1, (char*)(P) + tid * 16 + 8192); } while (0)
; #define STAGE_B(P, br, kt) do { const u16* _g = Bb + (long)(br) * ldb + (long)(kt) * 64; GLDS(_g + bo0, (char*)(P) + tid * 16); GLDS(_g + bo1, (char*)(P) + tid * 16 + 8192); } while (0)
; template <int EPI>
; DI void gemm_unit(const GemmP& g, int pm, int pn) {
;     ...
;   int r0_, c0_, r1_, c1_; stage_rc(tid * 16, r0_, c0_); stage_rc(tid * 16 + 8192, r1_, c1_);
;   const long ao0 = (long)r0_ * lda + c0_, ao1 = (long)r1_ * lda + c1_, bo0 = (long)r0_ * ldb + c0_, bo1 = (long)r1_ * ldb + c1_;
;   f32x4 acc[2][2][4][2];
; #pragma unroll
;   for (int a = 0; a < 2; ++a)
; #pragma unroll
;     for (int b = 0; b < 2; ++b)
; #pragma unroll
;       for (int m = 0; m < 4; ++m)
; #pragma unroll
;         for (int n = 0; n < 2; ++n) acc[a][b][m][n] = (f32x4){0.f, 0.f, 0.f, 0.f};
;   bf16x8 At[4][2], B0[2][2], B1[2][2];
;   const int nt = g.K >> 6;
;   STAGE_B(SB(0, 0), bcol, 0); STAGE_A(SA(0, 0), brow, 0);
;   STAGE_B(SB(0, 1), bcol + 128, 0); STAGE_A(SA(0, 1), brow + 128, 0);
;     ...
;     const int hc0 = pn * 128 + wc * 32 + fq * 4;
; #pragma unroll
;     for (int ai = 0; ai < 2; ++ai)
; #pragma unroll
;       for (int m = 0; m < 4; ++m) {
;         u16* rowp = g.Cb + (size_t)(row0 + ai * 128 + m * 16) * g.ldc + hc0;
; #pragma unroll
;         for (int n = 0; n < 2; ++n) {
;           const f32x4 gv = acc[ai][0][m][n], uv = acc[ai][1][m][n];
;           float hv[4];
; #pragma unroll
;           for (int e = 0; e < 4; ++e) hv[e] = gv[e] * __builtin_amdgcn_rcpf(1.f + __builtin_amdgcn_exp2f(-LOG2E * gv[e])) * uv[e];
;           uint2 o; o.x = pk2(hv[0], hv[1]); o.y = pk2(hv[2], hv[3]);
;           *(uint2*)(rowp + n * 16) = o;
;         }
;       }
	v_exp_f32_e32 v31, v31
	v_cvt_pk_bf16_f32 v26, v26, v27
	v_add_f32_e32 v30, 1.0, v30
	v_add_f32_e32 v31, 1.0, v31
	v_rcp_f32_e32 v30, v30
	v_rcp_f32_e32 v31, v31
	s_nop 0
	v_pk_mul_f32 v[28:29], v[28:29], v[30:31]
	s_nop 0
	v_pk_mul_f32 v[28:29], v[28:29], v[32:33]
	s_nop 0
	v_cvt_pk_bf16_f32 v27, v28, v29
	global_store_dwordx2 v[34:35], v[26:27], off
	v_mul_f32_e32 v26, 0xbfb8aa3b, v18
	v_mul_f32_e32 v27, 0xbfb8aa3b, v19
	v_exp_f32_e32 v26, v26
	v_exp_f32_e32 v27, v27
	v_add_f32_e32 v26, 1.0, v26
	v_add_f32_e32 v27, 1.0, v27
	v_rcp_f32_e32 v26, v26
	v_rcp_f32_e32 v27, v27
	s_nop 0
	v_pk_mul_f32 v[18:19], v[18:19], v[26:27]
	s_nop 0
	v_pk_mul_f32 v[18:19], v[18:19], v[22:23]
	v_mul_f32_e32 v22, 0xbfb8aa3b, v20
	v_mul_f32_e32 v23, 0xbfb8aa3b, v21
	v_exp_f32_e32 v22, v22
	v_exp_f32_e32 v23, v23
	v_cvt_pk_bf16_f32 v18, v18, v19
	v_add_f32_e32 v22, 1.0, v22
	v_add_f32_e32 v23, 1.0, v23
	v_rcp_f32_e32 v22, v22
	v_rcp_f32_e32 v23, v23
	s_nop 0
	v_pk_mul_f32 v[20:21], v[20:21], v[22:23]
	s_nop 0
	v_pk_mul_f32 v[20:21], v[20:21], v[24:25]
	s_nop 0
	v_cvt_pk_bf16_f32 v19, v20, v21
	global_store_dwordx2 v[34:35], v[18:19], off offset:32
	v_mad_i64_i32 v[18:19], s[8:9], v0, s10, v[130:131]
	v_mul_f32_e32 v0, 0xbfb8aa3b, v10
	v_exp_f32_e32 v0, v0
	v_lshl_add_u64 v[18:19], v[18:19], 0, v[132:133]
	v_readlane_b32 s8, v254, 1
	s_add_i32 s13, s13, s8
	v_add_f32_e32 v0, 1.0, v0
	v_rcp_f32_e32 v20, v0
	v_mul_f32_e32 v0, 0xbfb8aa3b, v11
	v_exp_f32_e32 v0, v0
	s_cmpk_gt_i32 s13, 0xaff
	v_readlane_b32 s9, v254, 2
	v_add_f32_e32 v0, 1.0, v0
	v_rcp_f32_e32 v21, v0
	v_mul_f32_e32 v0, 0xbfb8aa3b, v12
	v_exp_f32_e32 v0, v0
	v_pk_mul_f32 v[10:11], v[10:11], v[20:21]
	s_nop 0
	v_pk_mul_f32 v[10:11], v[10:11], v[14:15]
	v_add_f32_e32 v0, 1.0, v0
	v_rcp_f32_e32 v14, v0
	v_mul_f32_e32 v0, 0xbfb8aa3b, v13
	v_exp_f32_e32 v0, v0
	v_cvt_pk_bf16_f32 v10, v10, v11
	v_add_f32_e32 v0, 1.0, v0
	v_rcp_f32_e32 v15, v0
	v_mul_f32_e32 v0, 0xbfb8aa3b, v2
	v_exp_f32_e32 v0, v0
	v_pk_mul_f32 v[12:13], v[12:13], v[14:15]
	s_nop 0
	v_pk_mul_f32 v[12:13], v[12:13], v[16:17]
	v_add_f32_e32 v0, 1.0, v0
	v_cvt_pk_bf16_f32 v11, v12, v13
	global_store_dwordx2 v[18:19], v[10:11], off
	v_rcp_f32_e32 v10, v0
	v_mul_f32_e32 v0, 0xbfb8aa3b, v3
	v_exp_f32_e32 v0, v0
	s_nop 0
	v_add_f32_e32 v0, 1.0, v0
	v_rcp_f32_e32 v11, v0
	v_mul_f32_e32 v0, 0xbfb8aa3b, v4
	v_exp_f32_e32 v0, v0
	v_pk_mul_f32 v[2:3], v[2:3], v[10:11]
	s_nop 0
	v_pk_mul_f32 v[2:3], v[2:3], v[6:7]
	v_add_f32_e32 v0, 1.0, v0
	v_rcp_f32_e32 v6, v0
	v_mul_f32_e32 v0, 0xbfb8aa3b, v5
	v_exp_f32_e32 v0, v0
	v_cvt_pk_bf16_f32 v2, v2, v3
	v_add_f32_e32 v0, 1.0, v0
	v_rcp_f32_e32 v7, v0
	s_nop 0
	v_pk_mul_f32 v[4:5], v[4:5], v[6:7]
	s_nop 0
	v_pk_mul_f32 v[4:5], v[4:5], v[8:9]
	s_nop 0
	v_cvt_pk_bf16_f32 v3, v4, v5
	global_store_dwordx2 v[18:19], v[2:3], off offset:32
	s_cbranch_scc1 .LBB0_157
	s_mov_b32 s36, 1
	v_mov_b32_e32 v0, v201
	s_ashr_i32 s8, s13, 31
	v_ashrrev_i32_e32 v2, 31, v0
	v_lshrrev_b32_e32 v2, 26, v2
	v_add_u32_e32 v2, v0, v2
	v_ashrrev_i32_e32 v3, 6, v2
	v_bfe_i32 v2, v0, 27, 1
	v_lshlrev_b32_e32 v22, 4, v0
	v_lshrrev_b32_e32 v2, 22, v2
	v_add_u32_e32 v2, v22, v2
	v_and_b32_e32 v2, 0xfffffc00, v2
	v_sub_u32_e32 v2, v22, v2
	v_lshrrev_b32_e32 v4, 4, v2
	v_bitop3_b32 v4, v4, v2, 32 bitop3:0x6c
	v_ashrrev_i32_e32 v2, 31, v2
	v_lshrrev_b32_e32 v2, 26, v2
	v_lshlrev_b32_e32 v5, 3, v3
	v_add_u32_e32 v2, v4, v2
	s_lshr_b32 s8, s8, 29
	v_and_b32_e32 v5, -16, v5
	v_ashrrev_i32_e32 v6, 6, v2
	s_add_i32 s8, s13, s8
	v_add_u32_e32 v2, v6, v5
	v_mul_i32_i24_e32 v5, 64, v6
	s_ashr_i32 s9, s8, 3
	s_and_b32 s8, s8, -8
	v_lshlrev_b32_e32 v3, 5, v3
	v_sub_u32_e32 v4, v4, v5
	s_sub_i32 s8, s13, s8
	v_and_b32_e32 v3, 32, v3
	v_ashrrev_i16_sdwa v4, v218, sext(v4) dst_sel:DWORD dst_unused:UNUSED_PAD src0_sel:DWORD src1_sel:BYTE_0
	s_cmp_lt_i32 s8, 0
	s_movk_i32 s10, 0x161
	v_add_u32_sdwa v4, v3, sext(v4) dst_sel:DWORD dst_unused:UNUSED_PAD src0_sel:DWORD src1_sel:WORD_0
	v_add_u32_e32 v3, 0x2000, v22
	s_cselect_b32 s10, s10, 0x160
	v_ashrrev_i32_e32 v5, 31, v3
	s_mul_i32 s8, s10, s8
	v_lshrrev_b32_e32 v5, 22, v5
	s_add_i32 s8, s8, s9
	v_add_u32_e32 v5, v3, v5
	s_mul_hi_i32 s9, s8, 0x2e8ba2e9
	v_ashrrev_i32_e32 v5, 10, v5
	s_lshr_b32 s10, s9, 31
	s_ashr_i32 s9, s9, 6
	v_mul_i32_i24_e32 v6, 0x400, v5
	s_add_i32 s9, s9, s10
	v_sub_u32_e32 v3, v3, v6
	s_mul_i32 s10, s9, 0x160
	v_lshrrev_b32_e32 v6, 4, v3
	s_sub_i32 s8, s8, s10
	v_bitop3_b32 v3, v6, v3, 32 bitop3:0x6c
	s_sext_i32_i16 s10, s8
	v_ashrrev_i32_e32 v7, 31, v3
	s_bfe_u32 s10, s10, 0x3001c
	v_lshrrev_b32_e32 v7, 26, v7
	s_add_i32 s10, s8, s10
	v_add_u32_e32 v7, v3, v7
	s_sext_i32_i16 s11, s10
	s_and_b32 s10, s10, 0xfff8
	v_ashrrev_i32_e32 v8, 6, v7
	v_and_b32_e32 v7, 0xc0, v7
	s_sub_i32 s8, s8, s10
	s_ashr_i32 s22, s11, 3
	v_lshlrev_b32_e32 v6, 3, v5
	v_lshlrev_b32_e32 v5, 5, v5
	v_sub_u32_e32 v3, v3, v7
	s_sext_i32_i16 s8, s8
	v_and_b32_e32 v6, -16, v6
	v_and_b32_e32 v5, 32, v5
	v_ashrrev_i16_sdwa v3, v218, sext(v3) dst_sel:DWORD dst_unused:UNUSED_PAD src0_sel:DWORD src1_sel:BYTE_0
	s_lshl_b32 s16, s22, 8
	s_lshl_b32 s9, s9, 11
	s_lshl_b32 s8, s8, 8
	v_add_u32_e32 v6, v8, v6
	v_add_u32_sdwa v8, v5, sext(v3) dst_sel:DWORD dst_unused:UNUSED_PAD src0_sel:DWORD src1_sel:WORD_0
	v_ashrrev_i32_e32 v3, 31, v2
	s_ashr_i32 s17, s16, 31
	s_add_i32 s8, s8, s9
	v_ashrrev_i32_e32 v5, 31, v4
	v_lshlrev_b64 v[10:11], 11, v[2:3]
	s_lshl_b64 s[10:11], s[16:17], 12
	v_readlane_b32 s9, v254, 21
	v_ashrrev_i32_e32 v7, 31, v6
	v_lshl_add_u64 v[10:11], v[10:11], 0, v[4:5]
	s_add_u32 s14, s20, s10
	v_add_u32_e32 v150, s9, v22
	v_ashrrev_i32_e32 v9, 31, v8
	v_lshlrev_b64 v[12:13], 11, v[6:7]
	s_addc_u32 s15, s21, s11
; #define STAGE_A(P, br, kt) do { const u16* _g = Ab + (long)(br) * lda + (long)(kt) * 64; GLDS(_g + ao0, (char*)(P) + tid * 16); GLDS(_g + ao1, (char*)(P) + tid * 16 + 8192); } while (0)
; #define STAGE_B(P, br, kt) do { const u16* _g = Bb + (long)(br) * ldb + (long)(kt) * 64; GLDS(_g + bo0, (char*)(P) + tid * 16); GLDS(_g + bo1, (char*)(P) + tid * 16 + 8192); } while (0)
; template <int EPI>
; DI void gemm_unit(const GemmP& g, int pm, int pn) {
;     ...
;   int r0_, c0_, r1_, c1_; stage_rc(tid * 16, r0_, c0_); stage_rc(tid * 16 + 8192, r1_, c1_);
;   const long ao0 = (long)r0_ * lda + c0_, ao1 = (long)r1_ * lda + c1_, bo0 = (long)r0_ * ldb + c0_, bo1 = (long)r1_ * ldb + c1_;
;   f32x4 acc[2][2][4][2];
; #pragma unroll
;   for (int a = 0; a < 2; ++a)
; #pragma unroll
;     for (int b = 0; b < 2; ++b)
; #pragma unroll
;       for (int m = 0; m < 4; ++m)
; #pragma unroll
;         for (int n = 0; n < 2; ++n) acc[a][b][m][n] = (f32x4){0.f, 0.f, 0.f, 0.f};
;   bf16x8 At[4][2], B0[2][2], B1[2][2];
;   const int nt = g.K >> 6;
;   STAGE_B(SB(0, 0), bcol, 0); STAGE_A(SA(0, 0), brow, 0);
;   STAGE_B(SB(0, 1), bcol + 128, 0); STAGE_A(SA(0, 1), brow + 128, 0);
	v_lshlrev_b64 v[24:25], 1, v[10:11]
	v_readfirstlane_b32 s9, v150
	v_add_u32_e32 v151, 0x2000, v150
	v_lshl_add_u64 v[12:13], v[12:13], 0, v[8:9]
	v_lshl_add_u64 v[10:11], s[14:15], 0, v[24:25]
	s_mov_b32 m0, s9
	v_readfirstlane_b32 s9, v151
	v_lshlrev_b64 v[26:27], 1, v[12:13]
	s_mov_b32 m0, s9
	s_ashr_i32 s9, s8, 31
	v_lshl_add_u64 v[12:13], s[14:15], 0, v[26:27]
	s_lshl_b64 s[14:15], s[8:9], 12
	s_add_u32 s24, s66, s14
	s_addc_u32 s25, s67, s15
	s_bitset1_b32 s16, 7
	s_ashr_i32 s17, s16, 31
	v_add_u32_e32 v153, 0, v22
	s_lshl_b64 s[16:17], s[16:17], 12
	v_readfirstlane_b32 s9, v153
	v_add_u32_e32 v154, 0x2000, v153
	s_add_u32 s16, s20, s16
	v_lshl_add_u64 v[14:15], s[24:25], 0, v[24:25]
	s_mov_b32 m0, s9
	v_readfirstlane_b32 s9, v154
	s_addc_u32 s17, s21, s17
	s_mov_b32 m0, s9
	v_lshl_add_u64 v[20:21], s[16:17], 0, v[24:25]
	v_readlane_b32 s9, v254, 22
	v_lshl_add_u64 v[18:19], s[16:17], 0, v[26:27]
	s_or_b32 s16, s8, 0x80
	v_add_u32_e32 v155, s9, v22
	s_ashr_i32 s17, s16, 31
	v_lshl_add_u64 v[16:17], s[24:25], 0, v[26:27]
	v_readfirstlane_b32 s9, v155
	v_add_u32_e32 v157, 0x2000, v155
	s_lshl_b64 s[16:17], s[16:17], 12
	s_mov_b32 m0, s9
	v_readfirstlane_b32 s9, v157
	s_add_u32 s16, s66, s16
	v_add_u32_e32 v158, 0x4000, v153
	s_mov_b32 m0, s9
	s_addc_u32 s17, s67, s17
	v_readfirstlane_b32 s9, v158
	v_add_u32_e32 v159, 0x6000, v153
	v_lshl_add_u64 v[130:131], s[16:17], 0, v[24:25]
	s_mov_b32 m0, s9
	v_readfirstlane_b32 s9, v159
	v_lshl_add_u64 v[132:133], s[16:17], 0, v[26:27]
	s_mov_b32 m0, s9
	v_ashrrev_i32_e32 v23, 8, v0
	s_branch .Lff_join
.LBB0_151:
	s_mov_b32 s36, 0
	v_mov_b32_e32 v0, v201
	s_ashr_i32 s8, s13, 31
	s_waitcnt vmcnt(0)
	v_ashrrev_i32_e32 v2, 31, v0
	v_lshrrev_b32_e32 v2, 26, v2
	v_add_u32_e32 v2, v0, v2
	v_ashrrev_i32_e32 v3, 6, v2
	v_bfe_i32 v2, v0, 27, 1
	v_lshlrev_b32_e32 v22, 4, v0
	v_lshrrev_b32_e32 v2, 22, v2
	v_add_u32_e32 v2, v22, v2
	v_and_b32_e32 v2, 0xfffffc00, v2
	v_sub_u32_e32 v2, v22, v2
	v_lshrrev_b32_e32 v4, 4, v2
	v_bitop3_b32 v4, v4, v2, 32 bitop3:0x6c
	v_ashrrev_i32_e32 v2, 31, v2
	v_lshrrev_b32_e32 v2, 26, v2
	v_lshlrev_b32_e32 v5, 3, v3
	v_add_u32_e32 v2, v4, v2
	s_lshr_b32 s8, s8, 29
	v_and_b32_e32 v5, -16, v5
	v_ashrrev_i32_e32 v6, 6, v2
	s_add_i32 s8, s13, s8
	v_add_u32_e32 v2, v6, v5
	v_mul_i32_i24_e32 v5, 64, v6
	s_ashr_i32 s9, s8, 3
	s_and_b32 s8, s8, -8
	v_lshlrev_b32_e32 v3, 5, v3
	v_sub_u32_e32 v4, v4, v5
	s_sub_i32 s8, s13, s8
	v_and_b32_e32 v3, 32, v3
	v_ashrrev_i16_sdwa v4, v218, sext(v4) dst_sel:DWORD dst_unused:UNUSED_PAD src0_sel:DWORD src1_sel:BYTE_0
	s_cmp_lt_i32 s8, 0
	s_movk_i32 s10, 0x161
	v_add_u32_sdwa v4, v3, sext(v4) dst_sel:DWORD dst_unused:UNUSED_PAD src0_sel:DWORD src1_sel:WORD_0
	v_add_u32_e32 v3, 0x2000, v22
	s_cselect_b32 s10, s10, 0x160
	v_ashrrev_i32_e32 v5, 31, v3
	s_mul_i32 s8, s10, s8
	v_lshrrev_b32_e32 v5, 22, v5
	s_add_i32 s8, s8, s9
	v_add_u32_e32 v5, v3, v5
	s_mul_hi_i32 s9, s8, 0x2e8ba2e9
	v_ashrrev_i32_e32 v5, 10, v5
	s_lshr_b32 s10, s9, 31
	s_ashr_i32 s9, s9, 6
	v_mul_i32_i24_e32 v6, 0x400, v5
	s_add_i32 s9, s9, s10
	v_sub_u32_e32 v3, v3, v6
	s_mul_i32 s10, s9, 0x160
	v_lshrrev_b32_e32 v6, 4, v3
	s_sub_i32 s8, s8, s10
	v_bitop3_b32 v3, v6, v3, 32 bitop3:0x6c
	s_sext_i32_i16 s10, s8
	v_ashrrev_i32_e32 v7, 31, v3
	s_bfe_u32 s10, s10, 0x3001c
	v_lshrrev_b32_e32 v7, 26, v7
	s_add_i32 s10, s8, s10
	v_add_u32_e32 v7, v3, v7
	s_sext_i32_i16 s11, s10
	s_and_b32 s10, s10, 0xfff8
	v_ashrrev_i32_e32 v8, 6, v7
	v_and_b32_e32 v7, 0xc0, v7
	s_sub_i32 s8, s8, s10
	s_ashr_i32 s22, s11, 3
	v_lshlrev_b32_e32 v6, 3, v5
	v_lshlrev_b32_e32 v5, 5, v5
	v_sub_u32_e32 v3, v3, v7
	s_sext_i32_i16 s8, s8
	v_and_b32_e32 v6, -16, v6
	v_and_b32_e32 v5, 32, v5
	v_ashrrev_i16_sdwa v3, v218, sext(v3) dst_sel:DWORD dst_unused:UNUSED_PAD src0_sel:DWORD src1_sel:BYTE_0
	s_lshl_b32 s16, s22, 8
	s_lshl_b32 s9, s9, 11
	s_lshl_b32 s8, s8, 8
	v_add_u32_e32 v6, v8, v6
	v_add_u32_sdwa v8, v5, sext(v3) dst_sel:DWORD dst_unused:UNUSED_PAD src0_sel:DWORD src1_sel:WORD_0
	v_ashrrev_i32_e32 v3, 31, v2
	s_ashr_i32 s17, s16, 31
	s_add_i32 s8, s8, s9
	v_ashrrev_i32_e32 v5, 31, v4
	v_lshlrev_b64 v[10:11], 11, v[2:3]
	s_lshl_b64 s[10:11], s[16:17], 12
	v_readlane_b32 s9, v254, 21
	v_ashrrev_i32_e32 v7, 31, v6
	v_lshl_add_u64 v[10:11], v[10:11], 0, v[4:5]
	s_add_u32 s14, s20, s10
	v_add_u32_e32 v150, s9, v22
	v_ashrrev_i32_e32 v9, 31, v8
	v_lshlrev_b64 v[12:13], 11, v[6:7]
	s_addc_u32 s15, s21, s11
	v_lshlrev_b64 v[24:25], 1, v[10:11]
	v_readfirstlane_b32 s9, v150
	v_add_u32_e32 v151, 0x2000, v150
	v_lshl_add_u64 v[12:13], v[12:13], 0, v[8:9]
	v_lshl_add_u64 v[10:11], s[14:15], 0, v[24:25]
	s_mov_b32 m0, s9
	v_readfirstlane_b32 s9, v151
	global_load_lds_dwordx4 v[10:11], off
	v_lshlrev_b64 v[26:27], 1, v[12:13]
	s_mov_b32 m0, s9
	s_ashr_i32 s9, s8, 31
	v_lshl_add_u64 v[12:13], s[14:15], 0, v[26:27]
	s_lshl_b64 s[14:15], s[8:9], 12
	s_add_u32 s24, s66, s14
	s_addc_u32 s25, s67, s15
	s_bitset1_b32 s16, 7
	s_ashr_i32 s17, s16, 31
	v_add_u32_e32 v153, 0, v22
	s_lshl_b64 s[16:17], s[16:17], 12
	v_readfirstlane_b32 s9, v153
	v_add_u32_e32 v154, 0x2000, v153
	s_add_u32 s16, s20, s16
	global_load_lds_dwordx4 v[12:13], off
	v_lshl_add_u64 v[14:15], s[24:25], 0, v[24:25]
	s_mov_b32 m0, s9
	v_readfirstlane_b32 s9, v154
	s_addc_u32 s17, s21, s17
	global_load_lds_dwordx4 v[14:15], off
	s_mov_b32 m0, s9
	v_lshl_add_u64 v[20:21], s[16:17], 0, v[24:25]
	v_readlane_b32 s9, v254, 22
	v_lshl_add_u64 v[18:19], s[16:17], 0, v[26:27]
	s_or_b32 s16, s8, 0x80
	v_add_u32_e32 v155, s9, v22
	s_ashr_i32 s17, s16, 31
	v_lshl_add_u64 v[16:17], s[24:25], 0, v[26:27]
	v_readfirstlane_b32 s9, v155
	v_add_u32_e32 v157, 0x2000, v155
	s_lshl_b64 s[16:17], s[16:17], 12
	global_load_lds_dwordx4 v[16:17], off
	s_mov_b32 m0, s9
	v_readfirstlane_b32 s9, v157
	s_add_u32 s16, s66, s16
	v_add_u32_e32 v158, 0x4000, v153
	global_load_lds_dwordx4 v[20:21], off
	s_mov_b32 m0, s9
	s_addc_u32 s17, s67, s17
	v_readfirstlane_b32 s9, v158
	v_add_u32_e32 v159, 0x6000, v153
	global_load_lds_dwordx4 v[18:19], off
	v_lshl_add_u64 v[130:131], s[16:17], 0, v[24:25]
	s_mov_b32 m0, s9
	v_readfirstlane_b32 s9, v159
	global_load_lds_dwordx4 v[130:131], off
	v_lshl_add_u64 v[132:133], s[16:17], 0, v[26:27]
	s_mov_b32 m0, s9
	v_ashrrev_i32_e32 v23, 8, v0
	global_load_lds_dwordx4 v[132:133], off
; #define STAGE_A(P, br, kt) do { const u16* _g = Ab + (long)(br) * lda + (long)(kt) * 64; GLDS(_g + ao0, (char*)(P) + tid * 16); GLDS(_g + ao1, (char*)(P) + tid * 16 + 8192); } while (0)
; #define STAGE_B(P, br, kt) do { const u16* _g = Bb + (long)(br) * ldb + (long)(kt) * 64; GLDS(_g + bo0, (char*)(P) + tid * 16); GLDS(_g + bo1, (char*)(P) + tid * 16 + 8192); } while (0)
; #define WAIT_V(n) asm volatile("s_waitcnt vmcnt(" #n ")" ::: "memory")
; #define BAR __builtin_amdgcn_s_barrier()
; template <int EPI>
; DI void gemm_unit(const GemmP& g, int pm, int pn) {
;     ...
;   int r0_, c0_, r1_, c1_; stage_rc(tid * 16, r0_, c0_); stage_rc(tid * 16 + 8192, r1_, c1_);
;   const long ao0 = (long)r0_ * lda + c0_, ao1 = (long)r1_ * lda + c1_, bo0 = (long)r0_ * ldb + c0_, bo1 = (long)r1_ * ldb + c1_;
;   f32x4 acc[2][2][4][2];
; #pragma unroll
;   for (int a = 0; a < 2; ++a)
; #pragma unroll
;     for (int b = 0; b < 2; ++b)
; #pragma unroll
;       for (int m = 0; m < 4; ++m)
; #pragma unroll
;         for (int n = 0; n < 2; ++n) acc[a][b][m][n] = (f32x4){0.f, 0.f, 0.f, 0.f};
;   bf16x8 At[4][2], B0[2][2], B1[2][2];
;   const int nt = g.K >> 6;
;   STAGE_B(SB(0, 0), bcol, 0); STAGE_A(SA(0, 0), brow, 0);
;   STAGE_B(SB(0, 1), bcol + 128, 0); STAGE_A(SA(0, 1), brow + 128, 0);
;   if (wr == 1) BAR;
;   WAIT_V(4); BAR;
;   STAGE_B(SB(1, 0), bcol, 1); STAGE_A(SA(1, 0), brow, 1); STAGE_B(SB(1, 1), bcol + 128, 1);
;   WAIT_V(6); BAR;
.Lff_join:
	v_cmp_eq_u32_e32 vcc, 1, v23
	s_and_saveexec_b64 s[16:17], vcc
	s_cbranch_execz .LBB0_153
	s_barrier
.LBB0_153:
	s_or_b64 exec, exec, s[16:17]
	v_readlane_b32 s16, v254, 23
	s_mov_b64 s[24:25], 0x80
	v_lshl_add_u64 v[10:11], v[10:11], 0, s[24:25]
	v_add_u32_e32 v160, s16, v22
	v_add_u32_e32 v161, 0x2000, v160
	v_readfirstlane_b32 s9, v160
	s_mov_b32 m0, s9
	v_readfirstlane_b32 s9, v161
	v_add_u32_e32 v162, 0x8000, v153
	s_cmp_eq_u32 s36, 0
	s_cbranch_scc1 .Lff_w4_a
	s_waitcnt vmcnt(20)
	s_branch .Lff_w4_b
.Lff_w4_a:
	s_waitcnt vmcnt(4)
.Lff_w4_b:
	s_barrier
	global_load_lds_dwordx4 v[10:11], off
	v_lshl_add_u64 v[10:11], v[12:13], 0, s[24:25]
	s_mov_b32 m0, s9
	v_readfirstlane_b32 s9, v162
	v_add_u32_e32 v163, 0xa000, v153
	v_readlane_b32 s17, v254, 24
	global_load_lds_dwordx4 v[10:11], off
	v_lshl_add_u64 v[10:11], v[14:15], 0, s[24:25]
	s_mov_b32 m0, s9
	v_readfirstlane_b32 s9, v163
	v_add_u32_e32 v164, s17, v22
	global_load_lds_dwordx4 v[10:11], off
	v_lshl_add_u64 v[10:11], v[16:17], 0, s[24:25]
	s_mov_b32 m0, s9
	v_readfirstlane_b32 s9, v164
	v_add_u32_e32 v165, 0x2000, v164
	global_load_lds_dwordx4 v[10:11], off
	v_lshl_add_u64 v[10:11], v[20:21], 0, s[24:25]
	s_mov_b32 m0, s9
	v_readfirstlane_b32 s9, v165
	global_load_lds_dwordx4 v[10:11], off
	v_lshl_add_u64 v[10:11], v[18:19], 0, s[24:25]
	s_mov_b32 m0, s9
	v_and_b32_e32 v142, 15, v0
	global_load_lds_dwordx4 v[10:11], off
	v_bfe_u32 v144, v0, 4, 2
	v_lshlrev_b32_e32 v13, 2, v0
	v_lshlrev_b32_e32 v10, 4, v144
	v_lshlrev_b32_e32 v11, 6, v142
	v_and_b32_e32 v13, 32, v13
	v_bitop3_b32 v11, v10, v13, v11 bitop3:0x36
	v_readlane_b32 s9, v254, 21
	v_add_u32_e32 v16, s16, v11
	v_add_u32_e32 v17, s17, v11
	v_add_u32_e32 v14, s9, v11
	v_readlane_b32 s9, v254, 22
	v_add_u32_e32 v19, 0, v11
	s_add_u32 s10, s19, s10
	v_add_u32_e32 v15, s9, v11
	v_lshlrev_b32_e32 v11, 6, v0
	s_movk_i32 s9, 0x3c0
	v_and_or_b32 v10, v11, s9, v10
	s_addc_u32 s11, s18, s11
	v_lshlrev_b64 v[2:3], 12, v[2:3]
	v_xad_u32 v13, v10, v13, 0
	v_lshl_add_u64 v[10:11], s[10:11], 0, v[2:3]
	v_lshlrev_b64 v[4:5], 1, v[4:5]
	v_lshlrev_b64 v[6:7], 12, v[6:7]
	v_lshl_add_u64 v[2:3], s[14:15], 0, v[2:3]
	v_bfe_u32 v143, v0, 6, 2
	s_cmp_eq_u32 s36, 0
	s_cbranch_scc1 .Lff_w6_a
	s_waitcnt vmcnt(22)
	s_branch .Lff_w6_b
.Lff_w6_a:
	s_waitcnt vmcnt(6)
.Lff_w6_b:
	v_lshlrev_b32_e32 v18, 13, v23
	v_lshlrev_b64 v[8:9], 1, v[8:9]
	v_lshl_add_u64 v[138:139], v[2:3], 0, v[4:5]
	v_lshl_add_u64 v[2:3], s[14:15], 0, v[6:7]
	v_lshlrev_b32_e32 v12, 12, v143
	v_or_b32_e32 v20, 0x800, v18
	v_or_b32_e32 v21, 0x1000, v18
	v_or_b32_e32 v22, 0x1800, v18
	v_lshl_add_u64 v[134:135], v[10:11], 0, v[4:5]
	v_lshl_add_u64 v[10:11], s[10:11], 0, v[6:7]
	v_lshl_add_u64 v[140:141], v[2:3], 0, v[8:9]
	v_mov_b32_e32 v2, 0
	v_lshlrev_b32_e32 v145, 6, v23
	v_lshl_add_u64 v[136:137], v[10:11], 0, v[8:9]
	s_mov_b32 s9, -2
	v_add_u32_e32 v167, v14, v12
	v_add_u32_e32 v149, v19, v18
	v_add_u32_e32 v148, v13, v20
	v_add_u32_e32 v147, v13, v21
	v_add_u32_e32 v146, v13, v22
	v_add_u32_e32 v166, v15, v12
	v_add_u32_e32 v156, v16, v12
	v_add_u32_e32 v152, v17, v12
	v_mov_b32_e32 v3, v2
	v_mov_b32_e32 v4, v2
	v_mov_b32_e32 v5, v2
	v_mov_b32_e32 v6, v2
	v_mov_b32_e32 v7, v2
	v_mov_b32_e32 v8, v2
	v_mov_b32_e32 v9, v2
	v_mov_b32_e32 v10, v2
	v_mov_b32_e32 v11, v2
	v_mov_b32_e32 v12, v2
	v_mov_b32_e32 v13, v2
	v_mov_b32_e32 v14, v2
	v_mov_b32_e32 v15, v2
	v_mov_b32_e32 v16, v2
	v_mov_b32_e32 v17, v2
	v_mov_b32_e32 v18, v2
	v_mov_b32_e32 v19, v2
	v_mov_b32_e32 v20, v2
	v_mov_b32_e32 v21, v2
	v_mov_b32_e32 v22, v2
	v_mov_b32_e32 v23, v2
	v_mov_b32_e32 v24, v2
	v_mov_b32_e32 v25, v2
	v_mov_b32_e32 v26, v2
	v_mov_b32_e32 v27, v2
	v_mov_b32_e32 v28, v2
	v_mov_b32_e32 v29, v2
	v_mov_b32_e32 v30, v2
	v_mov_b32_e32 v31, v2
	v_mov_b32_e32 v32, v2
	v_mov_b32_e32 v33, v2
	v_mov_b32_e32 v34, v2
	v_mov_b32_e32 v35, v2
	v_mov_b32_e32 v36, v2
	v_mov_b32_e32 v37, v2
	v_mov_b32_e32 v38, v2
	v_mov_b32_e32 v39, v2
	v_mov_b32_e32 v40, v2
	v_mov_b32_e32 v41, v2
	v_mov_b32_e32 v42, v2
	v_mov_b32_e32 v43, v2
	v_mov_b32_e32 v44, v2
	v_mov_b32_e32 v45, v2
	v_mov_b32_e32 v46, v2
	v_mov_b32_e32 v47, v2
	v_mov_b32_e32 v48, v2
	v_mov_b32_e32 v49, v2
	v_mov_b32_e32 v50, v2
	v_mov_b32_e32 v51, v2
	v_mov_b32_e32 v52, v2
	v_mov_b32_e32 v53, v2
	v_mov_b32_e32 v54, v2
	v_mov_b32_e32 v55, v2
	v_mov_b32_e32 v56, v2
	v_mov_b32_e32 v57, v2
	v_mov_b32_e32 v58, v2
	v_mov_b32_e32 v59, v2
	v_mov_b32_e32 v60, v2
	v_mov_b32_e32 v61, v2
	v_mov_b32_e32 v62, v2
	v_mov_b32_e32 v63, v2
	v_mov_b32_e32 v64, v2
	v_mov_b32_e32 v65, v2
	v_mov_b32_e32 v66, v2
	v_mov_b32_e32 v67, v2
	v_mov_b32_e32 v68, v2
	v_mov_b32_e32 v69, v2
	v_mov_b32_e32 v70, v2
	v_mov_b32_e32 v71, v2
	v_mov_b32_e32 v72, v2
	v_mov_b32_e32 v73, v2
	v_mov_b32_e32 v74, v2
	v_mov_b32_e32 v75, v2
	v_mov_b32_e32 v76, v2
	v_mov_b32_e32 v77, v2
	v_mov_b32_e32 v78, v2
	v_mov_b32_e32 v79, v2
	v_mov_b32_e32 v80, v2
	v_mov_b32_e32 v81, v2
	v_mov_b32_e32 v82, v2
	v_mov_b32_e32 v83, v2
	v_mov_b32_e32 v84, v2
	v_mov_b32_e32 v85, v2
	v_mov_b32_e32 v86, v2
	v_mov_b32_e32 v87, v2
	v_mov_b32_e32 v88, v2
	v_mov_b32_e32 v89, v2
	v_mov_b32_e32 v90, v2
	v_mov_b32_e32 v91, v2
	v_mov_b32_e32 v92, v2
	v_mov_b32_e32 v93, v2
	v_mov_b32_e32 v94, v2
	v_mov_b32_e32 v95, v2
	v_mov_b32_e32 v96, v2
	v_mov_b32_e32 v97, v2
	v_mov_b32_e32 v98, v2
	v_mov_b32_e32 v99, v2
	v_mov_b32_e32 v100, v2
	v_mov_b32_e32 v101, v2
	v_mov_b32_e32 v102, v2
	v_mov_b32_e32 v103, v2
	v_mov_b32_e32 v104, v2
	v_mov_b32_e32 v105, v2
	v_mov_b32_e32 v106, v2
	v_mov_b32_e32 v107, v2
	v_mov_b32_e32 v108, v2
	v_mov_b32_e32 v109, v2
	v_mov_b32_e32 v110, v2
	v_mov_b32_e32 v111, v2
	v_mov_b32_e32 v112, v2
	v_mov_b32_e32 v113, v2
	v_mov_b32_e32 v114, v2
	v_mov_b32_e32 v115, v2
	v_mov_b32_e32 v116, v2
	v_mov_b32_e32 v117, v2
	v_mov_b32_e32 v118, v2
	v_mov_b32_e32 v119, v2
	v_mov_b32_e32 v120, v2
	v_mov_b32_e32 v121, v2
	v_mov_b32_e32 v122, v2
	v_mov_b32_e32 v123, v2
	v_mov_b32_e32 v124, v2
	v_mov_b32_e32 v125, v2
	v_mov_b32_e32 v126, v2
	v_mov_b32_e32 v127, v2
	v_mov_b32_e32 v128, v2
	v_mov_b32_e32 v129, v2
	s_mov_b64 s[14:15], 0x9d00100
	s_mov_b64 s[16:17], 0x9d80100
	s_mov_b64 s[24:25], 0x9d00180
	s_mov_b64 s[26:27], 0x9d80180
	s_barrier
